# scan chunk loop reads its A'T / RT operand tiles right after the last early LDS read instead of in the middle of the MFMA chain (on top of P9 reverse order)
# baseline (speedup 1.0000x reference)
; #define LAS __attribute__((address_space(3)))
; __device__ __forceinline__ void scan_phase(LAS unsigned char* lds, const Args& a, const bf16_t* z, const bf16_t* lo, float* yraw) {
;     ...
;                 for (int j = 0; j < 4; ++j) {
;                     const LAS unsigned char* CB = lds + ((it & 1) * 4 + j) * S2_CHB;
;                     asm volatile("" ::: "memory");
;                     s16x4 sbf[4];
; #pragma unroll
;                     for (int kt = 0; kt < 4; ++kt) { u32x2 w; w.x = pk2(St[kt][0], St[kt][1]); w.y = pk2(St[kt][2], St[kt][3]); sbf[kt] = __builtin_bit_cast(s16x4, w); }
;                     const s16x4 vtf = *(const LAS s16x4*)(CB + S2_VT + (vt * 16 + l15) * 32 + g4 * 8);
;                     f32x4 sg = {0.f, 0.f, 0.f, 0.f};
;                     { const s16x4 wf = *(const LAS s16x4*)(CB + S2_WT + l15 * 32 + g4 * 8);
;                       sg = MFMA16K16(wf, vtf, sg);
; #pragma unroll
;                       for (int kt = 0; kt < 4; ++kt) { const s16x4 af = *(const LAS s16x4*)(CB + S2_APT + l15 * 144 + kt * 32 + g4 * 8); sg = MFMA16K16(af, sbf[kt], sg); } }
;                     s16x4 sgf; { u32x2 w; w.x = pk2(sg[0], sg[1]); w.y = pk2(sg[2], sg[3]); sgf = __builtin_bit_cast(s16x4, w); }
;                     f32x4 yy = {0.f, 0.f, 0.f, 0.f};
;                     { const s16x4 brf = *(const LAS s16x4*)(CB + S2_BRT + l15 * 32 + g4 * 8), krf = *(const LAS s16x4*)(CB + S2_KRT + l15 * 32 + g4 * 8);
;                       yy = MFMA16K16(krf, vtf, yy);
; #pragma unroll
;                       for (int kt = 0; kt < 4; ++kt) { const s16x4 rf = *(const LAS s16x4*)(CB + S2_RT + l15 * 144 + kt * 32 + g4 * 8); yy = MFMA16K16(rf, sbf[kt], yy); }
;                       yy = MFMA16K16(brf, sgf, yy); }
;                     { bf16_t* yp = (bf16_t*)yraw + ((size_t)b * SEQ + it * 64 + j * 16 + 4 * g4) * 512 + h * 64 + vt * 16 + l15;
; #pragma unroll
;                       for (int i = 0; i < 4; ++i) yp[(size_t)i * 512] = f2bf(yy[i]); }
; #pragma unroll
;                     for (int kt = 0; kt < 4; ++kt) {
;                         const f32x4 gc = *(const LAS f32x4*)(CB + S2_GC + (16 * kt + 4 * g4) * 4);
;                         const s16x4 b2f = *(const LAS s16x4*)(CB + S2_B2T + (16 * kt + l15) * 32 + g4 * 8), k2f = *(const LAS s16x4*)(CB + S2_K2T + (16 * kt + l15) * 32 + g4 * 8);
;                         f32x4 sn = St[kt] * gc;
.LBB0_864:
	v_add_u32_e32 v36, s24, v29
	v_add_u32_e32 v102, s24, v30
	v_add_u32_e32 v103, s24, v31
	v_add_u32_e32 v106, s24, v28
	v_add_u32_e32 v107, 0x800, v106
	ds_read2st64_b64 v[32:35], v102 offset0:9 offset1:10
	ds_read_b64 v[100:101], v36
	ds_read2st64_b64 v[36:39], v102 offset0:11 offset1:12
	ds_read_b128 v[40:43], v103
	ds_read2st64_b64 v[44:47], v102 offset0:15 offset1:16
	s_waitcnt lgkmcnt(3)
	v_mfma_f32_16x16x16_bf16 v[48:51], v[32:33], v[100:101], 0
	ds_read_b128 v[52:55], v103 offset:64
	ds_read2st64_b64 v[84:87], v102 offset0:13 offset1:14
	ds_read2st64_b64 v[88:91], v102 offset0:17 offset1:18
	ds_read_b128 v[96:99], v103 offset:128
	ds_read_b64 v[32:33], v102 offset:9728
	v_cvt_pk_bf16_f32 v104, v20, v21
	v_cvt_pk_bf16_f32 v105, v22, v23
	s_waitcnt lgkmcnt(6)
	v_pk_mul_f32 v[20:21], v[20:21], v[40:41]
	v_pk_mul_f32 v[22:23], v[22:23], v[42:43]
	s_waitcnt lgkmcnt(4)
	v_pk_mul_f32 v[40:41], v[8:9], v[52:53]
	v_pk_mul_f32 v[42:43], v[10:11], v[54:55]
	ds_read_b128 v[52:55], v103 offset:192
	ds_read2_b64 v[108:111], v106 offset1:4
	ds_read2_b64 v[112:115], v107 offset0:32 offset1:36
	ds_read2_b64 v[116:119], v106 offset0:8 offset1:12
	ds_read2_b64 v[120:123], v107 offset0:40 offset1:44
	s_waitcnt lgkmcnt(6)
	v_pk_mul_f32 v[96:97], v[12:13], v[96:97]
	v_pk_mul_f32 v[98:99], v[14:15], v[98:99]
	s_nop 0
	v_mfma_f32_16x16x16_bf16 v[40:43], v[88:89], v[100:101], v[40:43]
	s_waitcnt lgkmcnt(4)
	v_pk_mul_f32 v[52:53], v[16:17], v[52:53]
	v_pk_mul_f32 v[54:55], v[18:19], v[54:55]
	s_nop 0
	v_mfma_f32_16x16x16_bf16 v[88:91], v[90:91], v[100:101], v[96:99]
	v_cvt_pk_bf16_f32 v16, v16, v17
	v_cvt_pk_bf16_f32 v17, v18, v19
	s_addk_i32 s24, 0x3100
	s_nop 0
	v_mfma_f32_16x16x16_bf16 v[92:95], v[36:37], v[100:101], 0
	v_cvt_pk_bf16_f32 v36, v12, v13
	v_cvt_pk_bf16_f32 v37, v14, v15
	s_cmpk_eq_u32 s24, 0xc400
	v_mfma_f32_16x16x16_bf16 v[20:23], v[46:47], v[100:101], v[20:23]
	v_mfma_f32_16x16x16_bf16 v[52:55], v[32:33], v[100:101], v[52:55]
	s_nop 0
	v_cvt_pk_bf16_f32 v32, v8, v9
	v_cvt_pk_bf16_f32 v33, v10, v11
	s_waitcnt lgkmcnt(3)
	v_mfma_f32_16x16x16_bf16 v[46:49], v[108:109], v[104:105], v[48:51]
	s_waitcnt lgkmcnt(2)
	v_mfma_f32_16x16x16_bf16 v[92:95], v[112:113], v[104:105], v[92:95]
	v_mfma_f32_16x16x16_bf16 v[8:11], v[110:111], v[32:33], v[46:49]
	s_nop 4
	s_nop 0
	v_mfma_f32_16x16x16_bf16 v[12:15], v[114:115], v[32:33], v[92:95]
	s_nop 2
	s_nop 0
	s_waitcnt lgkmcnt(1)
	v_mfma_f32_16x16x16_bf16 v[8:11], v[116:117], v[36:37], v[8:11]
	s_waitcnt lgkmcnt(0)
	v_mfma_f32_16x16x16_bf16 v[12:15], v[120:121], v[36:37], v[12:15]
	v_mfma_f32_16x16x16_bf16 v[8:11], v[118:119], v[16:17], v[8:11]
	v_mfma_f32_16x16x16_bf16 v[12:15], v[122:123], v[16:17], v[12:15]
	s_nop 6
	v_cvt_pk_bf16_f32 v16, v8, v9
	v_cvt_pk_bf16_f32 v17, v10, v11
	s_nop 1
	v_mfma_f32_16x16x16_bf16 v[32:35], v[34:35], v[16:17], v[12:15]
	v_mfma_f32_16x16x16_bf16 v[20:23], v[38:39], v[16:17], v[20:23]
	v_mfma_f32_16x16x16_bf16 v[8:11], v[84:85], v[16:17], v[40:43]
	s_nop 5
	v_cvt_pk_bf16_f32 v32, v32, s0
	v_cvt_pk_bf16_f32 v33, v33, s0
	v_cvt_pk_bf16_f32 v34, v34, s0
	v_mfma_f32_16x16x16_bf16 v[12:15], v[86:87], v[16:17], v[88:91]
	v_cvt_pk_bf16_f32 v35, v35, s0
	global_store_short v[26:27], v32, off offset:-2048
	global_store_short v[26:27], v33, off offset:-1024
	global_store_short v[26:27], v34, off
	global_store_short v[26:27], v35, off offset:1024
	v_lshl_add_u64 v[26:27], v[26:27], 0, s[18:19]
	v_mfma_f32_16x16x16_bf16 v[16:19], v[44:45], v[16:17], v[52:55]
	s_cbranch_scc0 .LBB0_864
	s_add_i32 s10, s10, 1
	s_xor_b64 s[22:23], s[22:23], -1
	s_cmp_eq_u32 s10, 64
	v_lshl_add_u64 v[24:25], v[24:25], 0, s[20:21]
	s_barrier
	s_cbranch_scc0 .LBB0_863
	s_setprio 0
	s_mov_b64 s[22:23], 0
